# toeplitz expansion: 4 masked x4 loads + single wait instead of 16 serialized dword loads
# speedup vs baseline: 1.0302x; 1.0043x over previous
; DI u32x4 pack8(const float* v) { u32x4 w; w.x = pk2(v[0], v[1]); w.y = pk2(v[2], v[3]); w.z = pk2(v[4], v[5]); w.w = pk2(v[6], v[7]); return w; }
; DI void phase_toeplitz(const Params& P, int gtid, int nthr) {
;     ...
;     for (int idx = gtid; idx < S5G * 512 * 64; idx += nthr) {
;         const int kc = idx & 63, tp = (idx >> 6) & 511, g = idx >> 15, t = tp >> 4, p = tp & 15, s = kc >> 1, q0 = (kc & 1) * 8;
;         float v[8];
; #pragma unroll
;         for (int j = 0; j < 8; ++j) {
;             float x = 0.f;
;             if (s <= t) x += ktab[(((g * 2 + 0) * 32 + (t - s)) * 16 + p) * 16 + q0 + j];
;             if (s >= t) x += ktab[(((g * 2 + 1) * 32 + (s - t)) * 16 + p) * 16 + q0 + j];
;             v[j] = x;
;         }
;         *(u32x4*)(bt2 + ((size_t)g * 512 + tp) * 768 + kc * 8) = pack8(v);
;     }
.Ltz_tail:
	v_bfe_u32 v2, v4, 6, 9
	v_add_u32_e32 v4, s84, v4
	s_mov_b32 s0, 0xbffff
	v_lshl_or_b32 v2, v7, 9, v2
	v_cmp_lt_i32_e32 vcc, s0, v4
	v_readlane_b32 s0, v254, 11
	v_cvt_pk_bf16_f32 v8, v8, v10
	v_cvt_pk_bf16_f32 v9, v11, v12
	v_cvt_pk_bf16_f32 v10, v13, v14
	v_cvt_pk_bf16_f32 v11, v15, v16
	v_mad_i64_i32 v[2:3], s[12:13], v2, s92, v[0:1]
	s_or_b64 s[10:11], vcc, s[10:11]
	v_add_u32_e32 v6, s0, v6
	global_store_dwordx4 v[2:3], v[8:11], off
	s_andn2_b64 exec, exec, s[10:11]
	s_cbranch_execz .LBB0_380
.LBB0_348:
	v_lshrrev_b32_e32 v2, 6, v4
	v_bfe_u32 v11, v2, 4, 5
	v_ashrrev_i32_e32 v7, 15, v4
	v_sub_co_u32_e32 v2, vcc, v11, v5
	v_bfe_u32 v9, v4, 6, 4
	v_lshlrev_b32_e32 v12, 10, v7
	v_lshlrev_b32_e32 v2, 4, v2
	v_and_b32_e32 v10, 8, v6
	v_or3_b32 v2, v2, v12, v9
	v_lshl_or_b32 v2, v2, 4, v10
	s_xor_b64 s[12:13], vcc, -1
	v_ashrrev_i32_e32 v3, 31, v2
	v_sub_co_u32_e32 v11, vcc, v5, v11
	v_lshlrev_b32_e32 v11, 4, v11
	v_or3_b32 v9, v11, v12, v9
	s_xor_b64 s[14:15], vcc, -1
	v_lshl_or_b32 v9, v9, 4, v10
	v_or_b32_e32 v10, 0x2000, v9
	v_ashrrev_i32_e32 v11, 31, v10
	v_lshl_add_u64 v[34:35], v[2:3], 2, s[8:9]
	v_lshl_add_u64 v[36:37], v[10:11], 2, s[8:9]
	v_mov_b32_e32 v18, 0
	v_mov_b32_e32 v19, 0
	v_mov_b32_e32 v20, 0
	v_mov_b32_e32 v21, 0
	v_mov_b32_e32 v22, 0
	v_mov_b32_e32 v23, 0
	v_mov_b32_e32 v24, 0
	v_mov_b32_e32 v25, 0
	v_mov_b32_e32 v26, 0
	v_mov_b32_e32 v27, 0
	v_mov_b32_e32 v28, 0
	v_mov_b32_e32 v29, 0
	v_mov_b32_e32 v30, 0
	v_mov_b32_e32 v31, 0
	v_mov_b32_e32 v32, 0
	v_mov_b32_e32 v33, 0
	s_and_saveexec_b64 s[16:17], s[12:13]
	global_load_dwordx4 v[18:21], v[34:35], off
	global_load_dwordx4 v[22:25], v[34:35], off offset:16
	s_or_b64 exec, exec, s[16:17]
	s_and_saveexec_b64 s[16:17], s[14:15]
	global_load_dwordx4 v[26:29], v[36:37], off
	global_load_dwordx4 v[30:33], v[36:37], off offset:16
	s_or_b64 exec, exec, s[16:17]
	s_waitcnt vmcnt(0)
	v_add_f32_e32 v18, 0, v18
	v_add_f32_e32 v19, 0, v19
	v_add_f32_e32 v20, 0, v20
	v_add_f32_e32 v21, 0, v21
	v_add_f32_e32 v22, 0, v22
	v_add_f32_e32 v23, 0, v23
	v_add_f32_e32 v24, 0, v24
	v_add_f32_e32 v25, 0, v25
	v_add_f32_e32 v8, v18, v26
	v_add_f32_e32 v10, v19, v27
	v_add_f32_e32 v11, v20, v28
	v_add_f32_e32 v12, v21, v29
	v_add_f32_e32 v13, v22, v30
	v_add_f32_e32 v14, v23, v31
	v_add_f32_e32 v15, v24, v32
	v_add_f32_e32 v16, v25, v33
	s_branch .Ltz_tail
